# P18b: prologue first-tile waits behind the job set-up, sixth prologue load kept between the two waits
# speedup vs baseline: 1.0061x; 1.0061x over previous
; #define PG8_STAGE(bufoff, gbase, voff) do { _Pragma("unroll") for (int _i = 0; _i < 2; ++_i) { unsigned _vo = (voff)[_i]; asm volatile("" : "+v"(_vo));   \
;         __builtin_amdgcn_global_load_lds((const unsigned*)((const char*)(gbase) + _vo), (LAS unsigned*)(lds + (bufoff) + ldsw + _i * 8192), 16, 0, 0); } } while (0)
; #define PG8_WAIT_V(n) asm volatile("s_waitcnt vmcnt(" #n ")" ::: "memory")
; #define PG8_BAR __builtin_amdgcn_s_barrier()
; __device__ __forceinline__ void gemm_phase(LAS unsigned char* lds, const Call& C, const int tid, const Args& args) {
;     ...
;     if (wr == 1) PG8_BAR;
;     PG8_WAIT_V(2); PG8_BAR;
;     PG8_STAGE(PG8_SB(1, 0), cB + kstep, voffB); PG8_STAGE(PG8_SA(1, 0), cA + kstep, voffA); PG8_STAGE(PG8_SB(1, 1), cB + hstepB + kstep, voffB);
;     PG8_WAIT_V(6); PG8_BAR;
;     for (;;) {
;         next_unit(C, ui + 1, nxt.pm, nxt.pn, nxt.kp0, nxt.np, nxt.slice);
;         const bool has_next = nxt.pm >= 0;
;         const char* nA = has_next ? PG8_APTR(nxt) : cA; const char* nB = has_next ? PG8_BPTR(nxt) : cB;
;         const int nt = 2 * cur.np;
.LBB0_264:
	v_mov_b32_e32 v80, v242
	s_and_b32 s24, s12, 3
	s_lshl_b32 s27, s13, 6
	s_lshl_b32 s17, s13, 13
	s_lshl_b32 s13, s24, 5
	s_nop 0
	v_writelane_b32 v254, s13, 59
	s_lshl_b32 s13, s24, 12
	v_mov_b32_e32 v80, v242
	s_add_i32 m0, s20, 0x1e000
	s_cmpk_lt_u32 s5, 0x100
	v_mov_b32_e32 v80, v244
	s_cselect_b64 s[80:81], -1, 0
	s_bitcmp0_b32 s5, 6
	s_mov_b32 s97, s29
	v_lshl_add_u64 v[0:1], s[34:35], 0, v[80:81]
	s_cselect_b64 s[34:35], -1, 0
	s_lshl_b32 s25, s24, 4
	v_writelane_b32 v254, s34, 60
	s_add_i32 s25, s25, 0
	s_add_i32 s25, s25, 0x20400
	v_writelane_b32 v254, s35, 61
	s_lshl_b32 s12, s12, 5
	v_writelane_b32 v254, s25, 62
	s_cmp_lt_u32 s5, 64
	v_writelane_b32 v254, s12, 63
	s_cselect_b64 s[34:35], -1, 0
	v_writelane_b32 v255, s34, 0
	s_ashr_i32 s53, s11, 31
	s_ashr_i32 s51, s21, 31
	v_readlane_b32 s47, v254, 38
	s_lshl_b32 s12, s24, 6
	v_readlane_b32 s24, v254, 23
	v_writelane_b32 v255, s35, 1
	s_mul_i32 s5, s47, s42
	v_readlane_b32 s25, v254, 24
	s_add_u32 s12, s24, s12
	v_readlane_b32 s43, v254, 16
	v_writelane_b32 v255, s12, 2
	s_addc_u32 s12, s25, 0
	s_mul_i32 s5, s5, s43
	v_writelane_b32 v255, s12, 3
	s_add_i32 s54, s5, s26
	s_lshr_b32 s5, s26, 3
	s_and_b32 s88, s26, 7
	v_writelane_b32 v255, s5, 4
	s_add_i32 s5, s5, 1
	s_lshl_b32 s45, s43, 2
	s_add_u32 s24, s48, 0x1000
	v_writelane_b32 v255, s5, 5
	s_addc_u32 s25, s49, 0
	v_writelane_b32 v255, s24, 6
	v_readlane_b32 s5, v254, 52
	s_add_i32 s5, s27, s5
	v_writelane_b32 v255, s25, 7
	v_writelane_b32 v255, s27, 8
	v_writelane_b32 v255, s5, 9
	s_ashr_i32 s5, s44, 1
	v_lshl_add_u64 v[0:1], v[0:1], 0, s[18:19]
	s_and_b32 s12, s44, 1
	s_bfe_i32 s28, s44, 0x10000
	s_lshl_b32 s24, s5, 3
	s_bitcmp1_b32 s44, 0
	v_writelane_b32 v255, s24, 10
	s_cselect_b64 s[24:25], -1, 0
	s_cmp_lg_u32 s5, 3
	s_cselect_b64 s[34:35], -1, 0
	s_cmp_eq_u32 s12, 0
	s_cselect_b64 s[36:37], -1, 0
	s_and_b64 s[38:39], s[36:37], exec
	s_movk_i32 s12, 0x1400
	s_movk_i32 s27, 0xc00
	s_cselect_b32 s12, 0x800, s12
	s_cselect_b32 s38, 0x400, s27
	s_cselect_b32 s39, s94, 0x400
	s_cselect_b32 s40, 0xc00, 0
	s_cselect_b32 s41, 0x800, 0
	s_or_b64 s[34:35], s[36:37], s[34:35]
	v_writelane_b32 v255, s34, 11
	s_lshl_b32 s27, s44, 12
	s_mov_b32 s55, s29
	v_writelane_b32 v255, s35, 12
	s_xor_b64 s[34:35], s[34:35], -1
	v_writelane_b32 v255, s34, 13
	s_mov_b32 s92, 0
	s_movk_i32 s46, 0x1600
	v_writelane_b32 v255, s35, 14
	s_lshl_b32 s34, s5, 12
	s_or_b32 s34, s38, s34
	s_ashr_i32 s35, s34, 31
	s_lshl_b64 s[34:35], s[34:35], 2
	s_add_u32 s34, s68, s34
	v_writelane_b32 v255, s27, 15
	s_addc_u32 s35, s69, s35
	s_and_b32 s27, s28, 0x30000
	v_writelane_b32 v255, s34, 16
	s_cmp_lt_i32 s5, 3
	v_writelane_b32 v255, s35, 17
	s_cselect_b64 s[34:35], -1, 0
	s_and_b64 s[24:25], s[24:25], s[34:35]
	v_cndmask_b32_e64 v2, 0, 1, s[24:25]
	v_writelane_b32 v255, s27, 18
	v_readfirstlane_b32 s24, v2
	s_add_i32 s5, s5, s24
	s_lshl_b32 s5, s5, 12
	v_cvt_f32_u32_e32 v2, s42
	s_or_b32 s24, s5, s41
	s_ashr_i32 s25, s24, 31
	s_lshl_b64 s[24:25], s[24:25], 2
	s_add_u32 s24, s68, s24
	v_rcp_iflag_f32_e32 v3, v2
	s_addc_u32 s25, s69, s25
	v_writelane_b32 v255, s24, 19
	v_readlane_b32 s27, v254, 41
	v_mul_f32_e32 v4, 0x4f7ffffe, v3
	v_writelane_b32 v255, s25, 20
	s_add_u32 s24, s48, 0x2c00
	s_addc_u32 s25, s49, 0
	v_writelane_b32 v255, s24, 21
	v_cvt_u32_f32_e32 v4, v4
	s_nop 0
	v_writelane_b32 v255, s25, 22
	s_add_u32 s24, s48, 0x5800
	s_addc_u32 s25, s49, 0
	v_writelane_b32 v255, s24, 23
	s_sub_i32 s5, 0, s42
	s_lshl_b32 s96, s43, 8
	v_writelane_b32 v255, s25, 24
	v_readfirstlane_b32 s24, v4
	v_cvt_f32_u32_e32 v4, s27
	s_mul_i32 s5, s5, s24
	s_mul_hi_u32 s5, s24, s5
	s_add_i32 s5, s24, s5
	v_mul_f32_e32 v3, v4, v3
	v_trunc_f32_e32 v3, v3
	v_fma_f32 v4, -v3, v2, v4
	v_cvt_u32_f32_e32 v3, v3
	v_writelane_b32 v255, s5, 25
	s_lshl_b64 s[82:83], s[96:97], 8
	v_cmp_ge_f32_e64 s[24:25], |v4|, v2
	v_and_b32_e32 v2, 48, v204
	v_lshlrev_b32_e32 v4, 6, v204
	s_movk_i32 s5, 0x3c0
	s_cmp_lg_u64 s[24:25], 0
	v_and_or_b32 v2, v4, s5, v2
	v_readfirstlane_b32 s5, v3
	s_addc_u32 s5, s5, 0
	s_abs_i32 s97, s43
	v_cvt_f32_u32_e32 v3, s97
	v_lshlrev_b32_e32 v4, 2, v204
	v_and_b32_e32 v4, 32, v4
	s_abs_i32 s93, s45
	v_bitop3_b32 v5, v2, s17, v4 bitop3:0xde
	v_rcp_iflag_f32_e32 v3, v3
	v_bitop3_b32 v245, s13, v2, v4 bitop3:0xf6
	v_cvt_f32_u32_e32 v2, s93
	s_sub_i32 s13, 0, s97
	v_mul_f32_e32 v3, 0x4f7ffffe, v3
	v_cvt_u32_f32_e32 v3, v3
	v_rcp_iflag_f32_e32 v2, v2
	s_and_b32 s5, s5, 31
	v_add_u32_e32 v246, 0, v5
	v_readfirstlane_b32 s17, v3
	v_mul_f32_e32 v2, 0x4f7ffffe, v2
	v_cvt_u32_f32_e32 v2, v2
	s_mul_i32 s13, s13, s17
	s_mul_hi_u32 s13, s17, s13
	s_add_i32 s13, s17, s13
	v_writelane_b32 v255, s13, 26
	s_sub_i32 s13, 0, s93
	v_readfirstlane_b32 s17, v2
	s_mul_i32 s13, s13, s17
	s_mul_hi_u32 s13, s17, s13
	v_writelane_b32 v255, s45, 27
	s_add_i32 s13, s17, s13
	v_writelane_b32 v255, s13, 28
	v_writelane_b32 v255, s5, 29
	s_mul_i32 s5, s5, s42
	s_sub_i32 s5, s27, s5
	v_writelane_b32 v255, s5, 30
	s_ashr_i32 s5, s43, 31
	v_writelane_b32 v255, s5, 31
	s_bfe_i32 s5, s43, 0x1001d
	v_writelane_b32 v255, s5, 32
	s_add_u32 s89, s22, 0x80
	v_writelane_b32 v255, s54, 33
	s_addc_u32 s94, 0, 0
	s_lshl_b32 s5, s12, 2
	v_writelane_b32 v255, s55, 34
	v_writelane_b32 v255, s5, 35
	s_lshl_b32 s12, s40, 2
	v_writelane_b32 v255, s12, 36
	s_lshl_b32 s28, s39, 2
	s_mov_b32 s27, s29
	v_writelane_b32 v255, s13, 37
	v_readlane_b32 s55, v254, 15
	s_waitcnt vmcnt(7)
	s_barrier
	global_load_lds_dwordx4 v[0:1], off
	s_waitcnt vmcnt(6)
	s_barrier
	s_branch .LBB0_267
